# nt on P3 h1 f32 residual-stream stores (read back only in P6)
# speedup vs baseline: 1.0304x; 1.0090x over previous
; DI unsigned cvt_pk(float lo, float hi) { const f32x2 v = {lo, hi}; return __builtin_bit_cast(unsigned, __builtin_convertvector(v, bf16v2)); }
;     __device__ __forceinline__ void operator()(const f32x4 (&acc)[2][2][4][2], const Unit& u, int wr, int wc, int fr, int fq) const {
;         const int col0 = u.pn * 256 + wc * 32 + 8 * fq, rowbase = u.pm * 256 + wr * 64 + fr;
; #pragma unroll
;         for (int ai = 0; ai < 2; ++ai)
; #pragma unroll
;             for (int m = 0; m < 4; ++m) {
;                 const int row = rowbase + ai * 128 + m * 16; const size_t off = (size_t)row * DM + col0;
;                 float q = 0.f;
; #pragma unroll
;                 for (int bj = 0; bj < 2; ++bj) {
;                     const f32x4 r0 = *(const f32x4*)(resid + off + bj * 128), r1 = *(const f32x4*)(resid + off + bj * 128 + 4);
;                     const f32x4 o0 = r0 + acc[ai][bj][m][0], o1 = r1 + acc[ai][bj][m][1];
;                     *(f32x4*)(out + off + bj * 128) = o0; *(f32x4*)(out + off + bj * 128 + 4) = o1;
;                     if (xb) {
;                         u32x4 w; w.x = cvt_pk(o0[0], o0[1]); w.y = cvt_pk(o0[2], o0[3]); w.z = cvt_pk(o1[0], o1[1]); w.w = cvt_pk(o1[2], o1[3]);
;                         *(u32x4*)(xb + off + bj * 128) = w;
;                         q += (o0[0] * o0[0] + o0[1] * o0[1]) + (o0[2] * o0[2] + o0[3] * o0[3]) + (o1[0] * o1[0] + o1[1] * o1[1]) + (o1[2] * o1[2] + o1[3] * o1[3]);
;                     }
;                 }
;                 if (xb) { q += __shfl_xor(q, 16); q += __shfl_xor(q, 32); if (fq == 0) ssq[(size_t)row * 16 + u.pn * 4 + wc] = q; }
.LBB0_753:
	v_lshl_add_u32 v146, s60, 8, v148
	v_lshl_or_b32 v145, s8, 8, v150
	v_lshl_add_u32 v144, v146, 10, v145
	v_lshlrev_b32_e32 v144, 2, v144
	s_lshl_b32 s60, s8, 4
	s_lshl_b32 s61, s33, 2
	s_add_i32 s60, s60, s61
	v_lshl_add_u32 v147, v146, 6, s60
	v_xor_b32_e32 v250, 16, v154
	v_xor_b32_e32 v251, 32, v154
	v_lshlrev_b32_e32 v250, 2, v250
	v_lshlrev_b32_e32 v251, 2, v251
	v_and_b32_e32 v155, 8, v154
	v_mul_i32_i24_e32 v155, 0xfffff002, v155
	v_add_u32_e32 v144, v144, v155
	v_add_u32_e32 v253, 0x8000, v144
	global_load_dwordx4 v[156:159], v144, s[52:53] nt
	global_load_dwordx4 v[160:163], v253, s[52:53] nt
	global_load_dwordx4 v[164:167], v144, s[52:53] offset:512 nt
	global_load_dwordx4 v[168:171], v253, s[52:53] offset:512 nt
	v_add_u32_e32 v252, 0x10000, v144
	v_add_u32_e32 v253, 0x8000, v252
	global_load_dwordx4 v[172:175], v252, s[52:53] nt
	global_load_dwordx4 v[176:179], v253, s[52:53] nt
	global_load_dwordx4 v[180:183], v252, s[52:53] offset:512 nt
	global_load_dwordx4 v[184:187], v253, s[52:53] offset:512 nt
	v_add_u32_e32 v252, 0x20000, v144
	v_add_u32_e32 v253, 0x8000, v252
	global_load_dwordx4 v[188:191], v252, s[52:53] nt
	global_load_dwordx4 v[192:195], v253, s[52:53] nt
	global_load_dwordx4 v[196:199], v252, s[52:53] offset:512 nt
	global_load_dwordx4 v[200:203], v253, s[52:53] offset:512 nt
	v_add_u32_e32 v252, 0x30000, v144
	v_add_u32_e32 v253, 0x8000, v252
	global_load_dwordx4 v[204:207], v252, s[52:53] nt
	global_load_dwordx4 v[208:211], v253, s[52:53] nt
	global_load_dwordx4 v[212:215], v252, s[52:53] offset:512 nt
	global_load_dwordx4 v[216:219], v253, s[52:53] offset:512 nt
	v_add_u32_e32 v252, 0x80000, v144
	v_add_u32_e32 v253, 0x8000, v252
	global_load_dwordx4 v[220:223], v252, s[52:53] nt
	global_load_dwordx4 v[226:229], v253, s[52:53] nt
	global_load_dwordx4 v[230:233], v252, s[52:53] offset:512 nt
	global_load_dwordx4 v[236:239], v253, s[52:53] offset:512 nt
	v_mov_b32_dpp v240, v120 row_ror:8 row_mask:0xf bank_mask:0xf
	v_mov_b32_dpp v241, v121 row_ror:8 row_mask:0xf bank_mask:0xf
	v_mov_b32_dpp v242, v122 row_ror:8 row_mask:0xf bank_mask:0xf
	v_mov_b32_dpp v243, v123 row_ror:8 row_mask:0xf bank_mask:0xf
	v_mov_b32_dpp v120, v124 row_ror:8 row_mask:0xf bank_mask:0x3
	v_mov_b32_dpp v121, v125 row_ror:8 row_mask:0xf bank_mask:0x3
	v_mov_b32_dpp v122, v126 row_ror:8 row_mask:0xf bank_mask:0x3
	v_mov_b32_dpp v123, v127 row_ror:8 row_mask:0xf bank_mask:0x3
	v_mov_b32_dpp v124, v240 quad_perm:[0,1,2,3] row_mask:0xf bank_mask:0xc
	v_mov_b32_dpp v125, v241 quad_perm:[0,1,2,3] row_mask:0xf bank_mask:0xc
	v_mov_b32_dpp v126, v242 quad_perm:[0,1,2,3] row_mask:0xf bank_mask:0xc
	v_mov_b32_dpp v127, v243 quad_perm:[0,1,2,3] row_mask:0xf bank_mask:0xc
	v_mov_b32_dpp v240, v112 row_ror:8 row_mask:0xf bank_mask:0xf
	v_mov_b32_dpp v241, v113 row_ror:8 row_mask:0xf bank_mask:0xf
	v_mov_b32_dpp v242, v114 row_ror:8 row_mask:0xf bank_mask:0xf
	v_mov_b32_dpp v243, v115 row_ror:8 row_mask:0xf bank_mask:0xf
	v_mov_b32_dpp v112, v116 row_ror:8 row_mask:0xf bank_mask:0x3
	v_mov_b32_dpp v113, v117 row_ror:8 row_mask:0xf bank_mask:0x3
	v_mov_b32_dpp v114, v118 row_ror:8 row_mask:0xf bank_mask:0x3
	v_mov_b32_dpp v115, v119 row_ror:8 row_mask:0xf bank_mask:0x3
	v_mov_b32_dpp v116, v240 quad_perm:[0,1,2,3] row_mask:0xf bank_mask:0xc
	v_mov_b32_dpp v117, v241 quad_perm:[0,1,2,3] row_mask:0xf bank_mask:0xc
	v_mov_b32_dpp v118, v242 quad_perm:[0,1,2,3] row_mask:0xf bank_mask:0xc
	v_mov_b32_dpp v119, v243 quad_perm:[0,1,2,3] row_mask:0xf bank_mask:0xc
	s_waitcnt vmcnt(16)
	v_pk_add_f32 v[124:125], v[124:125], v[156:157]
	v_pk_add_f32 v[126:127], v[126:127], v[158:159]
	v_pk_add_f32 v[120:121], v[120:121], v[160:161]
	v_pk_add_f32 v[122:123], v[122:123], v[162:163]
	v_pk_add_f32 v[116:117], v[116:117], v[164:165]
	v_pk_add_f32 v[118:119], v[118:119], v[166:167]
	v_pk_add_f32 v[112:113], v[112:113], v[168:169]
	v_pk_add_f32 v[114:115], v[114:115], v[170:171]
	v_add_u32_e32 v253, 0x8000, v144
	global_store_dwordx4 v144, v[124:127], s[54:55] nt
	global_store_dwordx4 v253, v[120:123], s[54:55] nt
	global_store_dwordx4 v144, v[116:119], s[54:55] offset:512 nt
	global_store_dwordx4 v253, v[112:115], s[54:55] offset:512 nt
	v_cvt_pk_bf16_f32 v240, v124, v125
	v_cvt_pk_bf16_f32 v241, v126, v127
	v_cvt_pk_bf16_f32 v242, v120, v121
	v_cvt_pk_bf16_f32 v243, v122, v123
	v_cvt_pk_bf16_f32 v244, v116, v117
	v_cvt_pk_bf16_f32 v245, v118, v119
	v_cvt_pk_bf16_f32 v246, v112, v113
	v_cvt_pk_bf16_f32 v247, v114, v115
	v_lshrrev_b32_e32 v254, 1, v144
	v_lshrrev_b32_e32 v253, 1, v253
	global_store_dwordx2 v254, v[240:241], s[40:41]
	global_store_dwordx2 v253, v[242:243], s[40:41]
	global_store_dwordx2 v254, v[244:245], s[40:41] offset:256
	global_store_dwordx2 v253, v[246:247], s[40:41] offset:256
	v_mul_f32_e32 v248, v124, v124
	v_mul_f32_e32 v249, v120, v120
	v_fmac_f32_e32 v248, v125, v125
	v_fmac_f32_e32 v249, v121, v121
	v_fmac_f32_e32 v248, v126, v126
	v_fmac_f32_e32 v249, v122, v122
	v_fmac_f32_e32 v248, v127, v127
	v_fmac_f32_e32 v249, v123, v123
	v_fmac_f32_e32 v248, v116, v116
	v_fmac_f32_e32 v249, v112, v112
	v_fmac_f32_e32 v248, v117, v117
	v_fmac_f32_e32 v249, v113, v113
	v_fmac_f32_e32 v248, v118, v118
	v_fmac_f32_e32 v249, v114, v114
	v_fmac_f32_e32 v248, v119, v119
	v_fmac_f32_e32 v249, v115, v115
	s_nop 1
	v_mov_b32_dpp v240, v248 row_ror:8 row_mask:0xf bank_mask:0xf
	v_mov_b32_dpp v241, v249 row_ror:8 row_mask:0xf bank_mask:0xf
	s_nop 0
	v_add_f32_e32 v248, v248, v240
	v_add_f32_e32 v249, v249, v241
	s_nop 1
	v_mov_b32_dpp v248, v249 quad_perm:[0,1,2,3] row_mask:0xf bank_mask:0xc
	ds_bpermute_b32 v249, v250, v248
	s_waitcnt lgkmcnt(0)
; DI unsigned cvt_pk(float lo, float hi) { const f32x2 v = {lo, hi}; return __builtin_bit_cast(unsigned, __builtin_convertvector(v, bf16v2)); }
;     __device__ __forceinline__ void operator()(const f32x4 (&acc)[2][2][4][2], const Unit& u, int wr, int wc, int fr, int fq) const {
;         const int col0 = u.pn * 256 + wc * 32 + 8 * fq, rowbase = u.pm * 256 + wr * 64 + fr;
; #pragma unroll
;         for (int ai = 0; ai < 2; ++ai)
; #pragma unroll
;             for (int m = 0; m < 4; ++m) {
;                 const int row = rowbase + ai * 128 + m * 16; const size_t off = (size_t)row * DM + col0;
;                 float q = 0.f;
; #pragma unroll
;                 for (int bj = 0; bj < 2; ++bj) {
;                     const f32x4 r0 = *(const f32x4*)(resid + off + bj * 128), r1 = *(const f32x4*)(resid + off + bj * 128 + 4);
;                     const f32x4 o0 = r0 + acc[ai][bj][m][0], o1 = r1 + acc[ai][bj][m][1];
;                     *(f32x4*)(out + off + bj * 128) = o0; *(f32x4*)(out + off + bj * 128 + 4) = o1;
;                     if (xb) {
;                         u32x4 w; w.x = cvt_pk(o0[0], o0[1]); w.y = cvt_pk(o0[2], o0[3]); w.z = cvt_pk(o1[0], o1[1]); w.w = cvt_pk(o1[2], o1[3]);
;                         *(u32x4*)(xb + off + bj * 128) = w;
;                         q += (o0[0] * o0[0] + o0[1] * o0[1]) + (o0[2] * o0[2] + o0[3] * o0[3]) + (o1[0] * o1[0] + o1[1] * o1[1]) + (o1[2] * o1[2] + o1[3] * o1[3]);
;                     }
;                 }
;                 if (xb) { q += __shfl_xor(q, 16); q += __shfl_xor(q, 32); if (fq == 0) ssq[(size_t)row * 16 + u.pn * 4 + wc] = q; }
	v_add_f32_e32 v248, v248, v249
	ds_bpermute_b32 v249, v251, v248
	s_waitcnt lgkmcnt(0)
	v_add_f32_e32 v248, v248, v249
	s_and_saveexec_b64 s[62:63], s[0:1]
	global_store_dword v147, v248, s[6:7]
	s_or_b64 exec, exec, s[62:63]
	v_add_u32_e32 v252, 0x90000, v144
	v_add_u32_e32 v253, 0x8000, v252
	global_load_dwordx4 v[156:159], v252, s[52:53] nt
	global_load_dwordx4 v[160:163], v253, s[52:53] nt
	global_load_dwordx4 v[164:167], v252, s[52:53] offset:512 nt
	global_load_dwordx4 v[168:171], v253, s[52:53] offset:512 nt
	v_mov_b32_dpp v240, v104 row_ror:8 row_mask:0xf bank_mask:0xf
	v_mov_b32_dpp v241, v105 row_ror:8 row_mask:0xf bank_mask:0xf
	v_mov_b32_dpp v242, v106 row_ror:8 row_mask:0xf bank_mask:0xf
	v_mov_b32_dpp v243, v107 row_ror:8 row_mask:0xf bank_mask:0xf
	v_mov_b32_dpp v104, v108 row_ror:8 row_mask:0xf bank_mask:0x3
	v_mov_b32_dpp v105, v109 row_ror:8 row_mask:0xf bank_mask:0x3
	v_mov_b32_dpp v106, v110 row_ror:8 row_mask:0xf bank_mask:0x3
	v_mov_b32_dpp v107, v111 row_ror:8 row_mask:0xf bank_mask:0x3
	v_mov_b32_dpp v108, v240 quad_perm:[0,1,2,3] row_mask:0xf bank_mask:0xc
	v_mov_b32_dpp v109, v241 quad_perm:[0,1,2,3] row_mask:0xf bank_mask:0xc
	v_mov_b32_dpp v110, v242 quad_perm:[0,1,2,3] row_mask:0xf bank_mask:0xc
	v_mov_b32_dpp v111, v243 quad_perm:[0,1,2,3] row_mask:0xf bank_mask:0xc
	v_mov_b32_dpp v240, v96 row_ror:8 row_mask:0xf bank_mask:0xf
	v_mov_b32_dpp v241, v97 row_ror:8 row_mask:0xf bank_mask:0xf
	v_mov_b32_dpp v242, v98 row_ror:8 row_mask:0xf bank_mask:0xf
	v_mov_b32_dpp v243, v99 row_ror:8 row_mask:0xf bank_mask:0xf
	v_mov_b32_dpp v96, v100 row_ror:8 row_mask:0xf bank_mask:0x3
	v_mov_b32_dpp v97, v101 row_ror:8 row_mask:0xf bank_mask:0x3
	v_mov_b32_dpp v98, v102 row_ror:8 row_mask:0xf bank_mask:0x3
	v_mov_b32_dpp v99, v103 row_ror:8 row_mask:0xf bank_mask:0x3
	v_mov_b32_dpp v100, v240 quad_perm:[0,1,2,3] row_mask:0xf bank_mask:0xc
	v_mov_b32_dpp v101, v241 quad_perm:[0,1,2,3] row_mask:0xf bank_mask:0xc
	v_mov_b32_dpp v102, v242 quad_perm:[0,1,2,3] row_mask:0xf bank_mask:0xc
	v_mov_b32_dpp v103, v243 quad_perm:[0,1,2,3] row_mask:0xf bank_mask:0xc
	s_waitcnt vmcnt(25)
	v_pk_add_f32 v[108:109], v[108:109], v[172:173]
	v_pk_add_f32 v[110:111], v[110:111], v[174:175]
	v_pk_add_f32 v[104:105], v[104:105], v[176:177]
	v_pk_add_f32 v[106:107], v[106:107], v[178:179]
	v_pk_add_f32 v[100:101], v[100:101], v[180:181]
	v_pk_add_f32 v[102:103], v[102:103], v[182:183]
	v_pk_add_f32 v[96:97], v[96:97], v[184:185]
	v_pk_add_f32 v[98:99], v[98:99], v[186:187]
	v_add_u32_e32 v252, 0x10000, v144
	v_add_u32_e32 v253, 0x8000, v252
	global_store_dwordx4 v252, v[108:111], s[54:55] nt
	global_store_dwordx4 v253, v[104:107], s[54:55] nt
	global_store_dwordx4 v252, v[100:103], s[54:55] offset:512 nt
	global_store_dwordx4 v253, v[96:99], s[54:55] offset:512 nt
	v_cvt_pk_bf16_f32 v240, v108, v109
	v_cvt_pk_bf16_f32 v241, v110, v111
	v_cvt_pk_bf16_f32 v242, v104, v105
	v_cvt_pk_bf16_f32 v243, v106, v107
	v_cvt_pk_bf16_f32 v244, v100, v101
	v_cvt_pk_bf16_f32 v245, v102, v103
	v_cvt_pk_bf16_f32 v246, v96, v97
	v_cvt_pk_bf16_f32 v247, v98, v99
	v_lshrrev_b32_e32 v254, 1, v252
	v_lshrrev_b32_e32 v253, 1, v253
	global_store_dwordx2 v254, v[240:241], s[40:41]
	global_store_dwordx2 v253, v[242:243], s[40:41]
	global_store_dwordx2 v254, v[244:245], s[40:41] offset:256
	global_store_dwordx2 v253, v[246:247], s[40:41] offset:256
	v_mul_f32_e32 v248, v108, v108
	v_mul_f32_e32 v249, v104, v104
	v_fmac_f32_e32 v248, v109, v109
	v_fmac_f32_e32 v249, v105, v105
	v_fmac_f32_e32 v248, v110, v110
	v_fmac_f32_e32 v249, v106, v106
	v_fmac_f32_e32 v248, v111, v111
	v_fmac_f32_e32 v249, v107, v107
	v_fmac_f32_e32 v248, v100, v100
	v_fmac_f32_e32 v249, v96, v96
	v_fmac_f32_e32 v248, v101, v101
	v_fmac_f32_e32 v249, v97, v97
	v_fmac_f32_e32 v248, v102, v102
	v_fmac_f32_e32 v249, v98, v98
	v_fmac_f32_e32 v248, v103, v103
	v_fmac_f32_e32 v249, v99, v99
	s_nop 1
	v_mov_b32_dpp v240, v248 row_ror:8 row_mask:0xf bank_mask:0xf
	v_mov_b32_dpp v241, v249 row_ror:8 row_mask:0xf bank_mask:0xf
	s_nop 0
	v_add_f32_e32 v248, v248, v240
	v_add_f32_e32 v249, v249, v241
	s_nop 1
	v_mov_b32_dpp v248, v249 quad_perm:[0,1,2,3] row_mask:0xf bank_mask:0xc
	ds_bpermute_b32 v249, v250, v248
	s_waitcnt lgkmcnt(0)
	v_add_f32_e32 v248, v248, v249
	ds_bpermute_b32 v249, v251, v248
	v_add_u32_e32 v254, 0x400, v147
	s_waitcnt lgkmcnt(0)
	v_add_f32_e32 v248, v248, v249
	s_and_saveexec_b64 s[62:63], s[0:1]
	global_store_dword v254, v248, s[6:7]
	s_or_b64 exec, exec, s[62:63]
	v_add_u32_e32 v252, 0xa0000, v144
	v_add_u32_e32 v253, 0x8000, v252
	global_load_dwordx4 v[172:175], v252, s[52:53] nt
	global_load_dwordx4 v[176:179], v253, s[52:53] nt
	global_load_dwordx4 v[180:183], v252, s[52:53] offset:512 nt
	global_load_dwordx4 v[184:187], v253, s[52:53] offset:512 nt
	v_mov_b32_dpp v240, v88 row_ror:8 row_mask:0xf bank_mask:0xf
	v_mov_b32_dpp v241, v89 row_ror:8 row_mask:0xf bank_mask:0xf
	v_mov_b32_dpp v242, v90 row_ror:8 row_mask:0xf bank_mask:0xf
	v_mov_b32_dpp v243, v91 row_ror:8 row_mask:0xf bank_mask:0xf
	v_mov_b32_dpp v88, v92 row_ror:8 row_mask:0xf bank_mask:0x3
	v_mov_b32_dpp v89, v93 row_ror:8 row_mask:0xf bank_mask:0x3
	v_mov_b32_dpp v90, v94 row_ror:8 row_mask:0xf bank_mask:0x3
	v_mov_b32_dpp v91, v95 row_ror:8 row_mask:0xf bank_mask:0x3
	v_mov_b32_dpp v92, v240 quad_perm:[0,1,2,3] row_mask:0xf bank_mask:0xc
	v_mov_b32_dpp v93, v241 quad_perm:[0,1,2,3] row_mask:0xf bank_mask:0xc
	v_mov_b32_dpp v94, v242 quad_perm:[0,1,2,3] row_mask:0xf bank_mask:0xc
	v_mov_b32_dpp v95, v243 quad_perm:[0,1,2,3] row_mask:0xf bank_mask:0xc
	v_mov_b32_dpp v240, v80 row_ror:8 row_mask:0xf bank_mask:0xf
	v_mov_b32_dpp v241, v81 row_ror:8 row_mask:0xf bank_mask:0xf
	v_mov_b32_dpp v242, v82 row_ror:8 row_mask:0xf bank_mask:0xf
	v_mov_b32_dpp v243, v83 row_ror:8 row_mask:0xf bank_mask:0xf
	v_mov_b32_dpp v80, v84 row_ror:8 row_mask:0xf bank_mask:0x3
	v_mov_b32_dpp v81, v85 row_ror:8 row_mask:0xf bank_mask:0x3
	v_mov_b32_dpp v82, v86 row_ror:8 row_mask:0xf bank_mask:0x3
	v_mov_b32_dpp v83, v87 row_ror:8 row_mask:0xf bank_mask:0x3
	v_mov_b32_dpp v84, v240 quad_perm:[0,1,2,3] row_mask:0xf bank_mask:0xc
	v_mov_b32_dpp v85, v241 quad_perm:[0,1,2,3] row_mask:0xf bank_mask:0xc
	v_mov_b32_dpp v86, v242 quad_perm:[0,1,2,3] row_mask:0xf bank_mask:0xc
	v_mov_b32_dpp v87, v243 quad_perm:[0,1,2,3] row_mask:0xf bank_mask:0xc
	s_waitcnt vmcnt(34)
; DI unsigned cvt_pk(float lo, float hi) { const f32x2 v = {lo, hi}; return __builtin_bit_cast(unsigned, __builtin_convertvector(v, bf16v2)); }
;     __device__ __forceinline__ void operator()(const f32x4 (&acc)[2][2][4][2], const Unit& u, int wr, int wc, int fr, int fq) const {
;         const int col0 = u.pn * 256 + wc * 32 + 8 * fq, rowbase = u.pm * 256 + wr * 64 + fr;
; #pragma unroll
;         for (int ai = 0; ai < 2; ++ai)
; #pragma unroll
;             for (int m = 0; m < 4; ++m) {
;                 const int row = rowbase + ai * 128 + m * 16; const size_t off = (size_t)row * DM + col0;
;                 float q = 0.f;
; #pragma unroll
;                 for (int bj = 0; bj < 2; ++bj) {
;                     const f32x4 r0 = *(const f32x4*)(resid + off + bj * 128), r1 = *(const f32x4*)(resid + off + bj * 128 + 4);
;                     const f32x4 o0 = r0 + acc[ai][bj][m][0], o1 = r1 + acc[ai][bj][m][1];
;                     *(f32x4*)(out + off + bj * 128) = o0; *(f32x4*)(out + off + bj * 128 + 4) = o1;
;                     if (xb) {
;                         u32x4 w; w.x = cvt_pk(o0[0], o0[1]); w.y = cvt_pk(o0[2], o0[3]); w.z = cvt_pk(o1[0], o1[1]); w.w = cvt_pk(o1[2], o1[3]);
;                         *(u32x4*)(xb + off + bj * 128) = w;
;                         q += (o0[0] * o0[0] + o0[1] * o0[1]) + (o0[2] * o0[2] + o0[3] * o0[3]) + (o1[0] * o1[0] + o1[1] * o1[1]) + (o1[2] * o1[2] + o1[3] * o1[3]);
;                     }
;                 }
;                 if (xb) { q += __shfl_xor(q, 16); q += __shfl_xor(q, 32); if (fq == 0) ssq[(size_t)row * 16 + u.pn * 4 + wc] = q; }
	v_pk_add_f32 v[92:93], v[92:93], v[188:189]
	v_pk_add_f32 v[94:95], v[94:95], v[190:191]
	v_pk_add_f32 v[88:89], v[88:89], v[192:193]
	v_pk_add_f32 v[90:91], v[90:91], v[194:195]
	v_pk_add_f32 v[84:85], v[84:85], v[196:197]
	v_pk_add_f32 v[86:87], v[86:87], v[198:199]
	v_pk_add_f32 v[80:81], v[80:81], v[200:201]
	v_pk_add_f32 v[82:83], v[82:83], v[202:203]
	v_add_u32_e32 v252, 0x20000, v144
	v_add_u32_e32 v253, 0x8000, v252
	global_store_dwordx4 v252, v[92:95], s[54:55] nt
	global_store_dwordx4 v253, v[88:91], s[54:55] nt
	global_store_dwordx4 v252, v[84:87], s[54:55] offset:512 nt
	global_store_dwordx4 v253, v[80:83], s[54:55] offset:512 nt
	v_cvt_pk_bf16_f32 v240, v92, v93
	v_cvt_pk_bf16_f32 v241, v94, v95
	v_cvt_pk_bf16_f32 v242, v88, v89
	v_cvt_pk_bf16_f32 v243, v90, v91
	v_cvt_pk_bf16_f32 v244, v84, v85
	v_cvt_pk_bf16_f32 v245, v86, v87
	v_cvt_pk_bf16_f32 v246, v80, v81
	v_cvt_pk_bf16_f32 v247, v82, v83
	v_lshrrev_b32_e32 v254, 1, v252
	v_lshrrev_b32_e32 v253, 1, v253
	global_store_dwordx2 v254, v[240:241], s[40:41]
	global_store_dwordx2 v253, v[242:243], s[40:41]
	global_store_dwordx2 v254, v[244:245], s[40:41] offset:256
	global_store_dwordx2 v253, v[246:247], s[40:41] offset:256
	v_mul_f32_e32 v248, v92, v92
	v_mul_f32_e32 v249, v88, v88
	v_fmac_f32_e32 v248, v93, v93
	v_fmac_f32_e32 v249, v89, v89
	v_fmac_f32_e32 v248, v94, v94
	v_fmac_f32_e32 v249, v90, v90
	v_fmac_f32_e32 v248, v95, v95
	v_fmac_f32_e32 v249, v91, v91
	v_fmac_f32_e32 v248, v84, v84
	v_fmac_f32_e32 v249, v80, v80
	v_fmac_f32_e32 v248, v85, v85
	v_fmac_f32_e32 v249, v81, v81
	v_fmac_f32_e32 v248, v86, v86
	v_fmac_f32_e32 v249, v82, v82
	v_fmac_f32_e32 v248, v87, v87
	v_fmac_f32_e32 v249, v83, v83
	s_nop 1
	v_mov_b32_dpp v240, v248 row_ror:8 row_mask:0xf bank_mask:0xf
	v_mov_b32_dpp v241, v249 row_ror:8 row_mask:0xf bank_mask:0xf
	s_nop 0
	v_add_f32_e32 v248, v248, v240
	v_add_f32_e32 v249, v249, v241
	s_nop 1
	v_mov_b32_dpp v248, v249 quad_perm:[0,1,2,3] row_mask:0xf bank_mask:0xc
	ds_bpermute_b32 v249, v250, v248
	s_waitcnt lgkmcnt(0)
	v_add_f32_e32 v248, v248, v249
	ds_bpermute_b32 v249, v251, v248
	v_add_u32_e32 v254, 0x800, v147
	s_waitcnt lgkmcnt(0)
	v_add_f32_e32 v248, v248, v249
	s_and_saveexec_b64 s[62:63], s[0:1]
	global_store_dword v254, v248, s[6:7]
	s_or_b64 exec, exec, s[62:63]
	v_add_u32_e32 v252, 0xb0000, v144
	v_add_u32_e32 v253, 0x8000, v252
	global_load_dwordx4 v[188:191], v252, s[52:53] nt
	global_load_dwordx4 v[192:195], v253, s[52:53] nt
	global_load_dwordx4 v[196:199], v252, s[52:53] offset:512 nt
	global_load_dwordx4 v[200:203], v253, s[52:53] offset:512 nt
	v_mov_b32_dpp v240, v72 row_ror:8 row_mask:0xf bank_mask:0xf
	v_mov_b32_dpp v241, v73 row_ror:8 row_mask:0xf bank_mask:0xf
	v_mov_b32_dpp v242, v74 row_ror:8 row_mask:0xf bank_mask:0xf
	v_mov_b32_dpp v243, v75 row_ror:8 row_mask:0xf bank_mask:0xf
	v_mov_b32_dpp v72, v76 row_ror:8 row_mask:0xf bank_mask:0x3
	v_mov_b32_dpp v73, v77 row_ror:8 row_mask:0xf bank_mask:0x3
	v_mov_b32_dpp v74, v78 row_ror:8 row_mask:0xf bank_mask:0x3
	v_mov_b32_dpp v75, v79 row_ror:8 row_mask:0xf bank_mask:0x3
	v_mov_b32_dpp v76, v240 quad_perm:[0,1,2,3] row_mask:0xf bank_mask:0xc
	v_mov_b32_dpp v77, v241 quad_perm:[0,1,2,3] row_mask:0xf bank_mask:0xc
	v_mov_b32_dpp v78, v242 quad_perm:[0,1,2,3] row_mask:0xf bank_mask:0xc
	v_mov_b32_dpp v79, v243 quad_perm:[0,1,2,3] row_mask:0xf bank_mask:0xc
	v_mov_b32_dpp v240, v64 row_ror:8 row_mask:0xf bank_mask:0xf
	v_mov_b32_dpp v241, v65 row_ror:8 row_mask:0xf bank_mask:0xf
	v_mov_b32_dpp v242, v66 row_ror:8 row_mask:0xf bank_mask:0xf
	v_mov_b32_dpp v243, v67 row_ror:8 row_mask:0xf bank_mask:0xf
	v_mov_b32_dpp v64, v68 row_ror:8 row_mask:0xf bank_mask:0x3
	v_mov_b32_dpp v65, v69 row_ror:8 row_mask:0xf bank_mask:0x3
	v_mov_b32_dpp v66, v70 row_ror:8 row_mask:0xf bank_mask:0x3
	v_mov_b32_dpp v67, v71 row_ror:8 row_mask:0xf bank_mask:0x3
	v_mov_b32_dpp v68, v240 quad_perm:[0,1,2,3] row_mask:0xf bank_mask:0xc
	v_mov_b32_dpp v69, v241 quad_perm:[0,1,2,3] row_mask:0xf bank_mask:0xc
	v_mov_b32_dpp v70, v242 quad_perm:[0,1,2,3] row_mask:0xf bank_mask:0xc
	v_mov_b32_dpp v71, v243 quad_perm:[0,1,2,3] row_mask:0xf bank_mask:0xc
	s_waitcnt vmcnt(43)
	v_pk_add_f32 v[76:77], v[76:77], v[204:205]
	v_pk_add_f32 v[78:79], v[78:79], v[206:207]
	v_pk_add_f32 v[72:73], v[72:73], v[208:209]
	v_pk_add_f32 v[74:75], v[74:75], v[210:211]
	v_pk_add_f32 v[68:69], v[68:69], v[212:213]
	v_pk_add_f32 v[70:71], v[70:71], v[214:215]
	v_pk_add_f32 v[64:65], v[64:65], v[216:217]
	v_pk_add_f32 v[66:67], v[66:67], v[218:219]
	v_add_u32_e32 v252, 0x30000, v144
	v_add_u32_e32 v253, 0x8000, v252
	global_store_dwordx4 v252, v[76:79], s[54:55] nt
	global_store_dwordx4 v253, v[72:75], s[54:55] nt
	global_store_dwordx4 v252, v[68:71], s[54:55] offset:512 nt
	global_store_dwordx4 v253, v[64:67], s[54:55] offset:512 nt
	v_cvt_pk_bf16_f32 v240, v76, v77
	v_cvt_pk_bf16_f32 v241, v78, v79
	v_cvt_pk_bf16_f32 v242, v72, v73
	v_cvt_pk_bf16_f32 v243, v74, v75
	v_cvt_pk_bf16_f32 v244, v68, v69
	v_cvt_pk_bf16_f32 v245, v70, v71
	v_cvt_pk_bf16_f32 v246, v64, v65
	v_cvt_pk_bf16_f32 v247, v66, v67
	v_lshrrev_b32_e32 v254, 1, v252
	v_lshrrev_b32_e32 v253, 1, v253
	global_store_dwordx2 v254, v[240:241], s[40:41]
	global_store_dwordx2 v253, v[242:243], s[40:41]
	global_store_dwordx2 v254, v[244:245], s[40:41] offset:256
	global_store_dwordx2 v253, v[246:247], s[40:41] offset:256
	v_mul_f32_e32 v248, v76, v76
	v_mul_f32_e32 v249, v72, v72
	v_fmac_f32_e32 v248, v77, v77
	v_fmac_f32_e32 v249, v73, v73
	v_fmac_f32_e32 v248, v78, v78
	v_fmac_f32_e32 v249, v74, v74
	v_fmac_f32_e32 v248, v79, v79
	v_fmac_f32_e32 v249, v75, v75
	v_fmac_f32_e32 v248, v68, v68
	v_fmac_f32_e32 v249, v64, v64
	v_fmac_f32_e32 v248, v69, v69
	v_fmac_f32_e32 v249, v65, v65
	v_fmac_f32_e32 v248, v70, v70
	v_fmac_f32_e32 v249, v66, v66
	v_fmac_f32_e32 v248, v71, v71
	v_fmac_f32_e32 v249, v67, v67
	s_nop 1
	v_mov_b32_dpp v240, v248 row_ror:8 row_mask:0xf bank_mask:0xf
	v_mov_b32_dpp v241, v249 row_ror:8 row_mask:0xf bank_mask:0xf
	s_nop 0
	v_add_f32_e32 v248, v248, v240
	v_add_f32_e32 v249, v249, v241
	s_nop 1
	v_mov_b32_dpp v248, v249 quad_perm:[0,1,2,3] row_mask:0xf bank_mask:0xc
	ds_bpermute_b32 v249, v250, v248
	s_waitcnt lgkmcnt(0)
; DI unsigned cvt_pk(float lo, float hi) { const f32x2 v = {lo, hi}; return __builtin_bit_cast(unsigned, __builtin_convertvector(v, bf16v2)); }
;     __device__ __forceinline__ void operator()(const f32x4 (&acc)[2][2][4][2], const Unit& u, int wr, int wc, int fr, int fq) const {
;         const int col0 = u.pn * 256 + wc * 32 + 8 * fq, rowbase = u.pm * 256 + wr * 64 + fr;
; #pragma unroll
;         for (int ai = 0; ai < 2; ++ai)
; #pragma unroll
;             for (int m = 0; m < 4; ++m) {
;                 const int row = rowbase + ai * 128 + m * 16; const size_t off = (size_t)row * DM + col0;
;                 float q = 0.f;
; #pragma unroll
;                 for (int bj = 0; bj < 2; ++bj) {
;                     const f32x4 r0 = *(const f32x4*)(resid + off + bj * 128), r1 = *(const f32x4*)(resid + off + bj * 128 + 4);
;                     const f32x4 o0 = r0 + acc[ai][bj][m][0], o1 = r1 + acc[ai][bj][m][1];
;                     *(f32x4*)(out + off + bj * 128) = o0; *(f32x4*)(out + off + bj * 128 + 4) = o1;
;                     if (xb) {
;                         u32x4 w; w.x = cvt_pk(o0[0], o0[1]); w.y = cvt_pk(o0[2], o0[3]); w.z = cvt_pk(o1[0], o1[1]); w.w = cvt_pk(o1[2], o1[3]);
;                         *(u32x4*)(xb + off + bj * 128) = w;
;                         q += (o0[0] * o0[0] + o0[1] * o0[1]) + (o0[2] * o0[2] + o0[3] * o0[3]) + (o1[0] * o1[0] + o1[1] * o1[1]) + (o1[2] * o1[2] + o1[3] * o1[3]);
;                     }
;                 }
;                 if (xb) { q += __shfl_xor(q, 16); q += __shfl_xor(q, 32); if (fq == 0) ssq[(size_t)row * 16 + u.pn * 4 + wc] = q; }
	v_add_f32_e32 v248, v248, v249
	ds_bpermute_b32 v249, v251, v248
	v_add_u32_e32 v254, 0xc00, v147
	s_waitcnt lgkmcnt(0)
	v_add_f32_e32 v248, v248, v249
	s_and_saveexec_b64 s[62:63], s[0:1]
	global_store_dword v254, v248, s[6:7]
	s_or_b64 exec, exec, s[62:63]
	v_mov_b32_dpp v240, v56 row_ror:8 row_mask:0xf bank_mask:0xf
	v_mov_b32_dpp v241, v57 row_ror:8 row_mask:0xf bank_mask:0xf
	v_mov_b32_dpp v242, v58 row_ror:8 row_mask:0xf bank_mask:0xf
	v_mov_b32_dpp v243, v59 row_ror:8 row_mask:0xf bank_mask:0xf
	v_mov_b32_dpp v56, v60 row_ror:8 row_mask:0xf bank_mask:0x3
	v_mov_b32_dpp v57, v61 row_ror:8 row_mask:0xf bank_mask:0x3
	v_mov_b32_dpp v58, v62 row_ror:8 row_mask:0xf bank_mask:0x3
	v_mov_b32_dpp v59, v63 row_ror:8 row_mask:0xf bank_mask:0x3
	v_mov_b32_dpp v60, v240 quad_perm:[0,1,2,3] row_mask:0xf bank_mask:0xc
	v_mov_b32_dpp v61, v241 quad_perm:[0,1,2,3] row_mask:0xf bank_mask:0xc
	v_mov_b32_dpp v62, v242 quad_perm:[0,1,2,3] row_mask:0xf bank_mask:0xc
	v_mov_b32_dpp v63, v243 quad_perm:[0,1,2,3] row_mask:0xf bank_mask:0xc
	v_mov_b32_dpp v240, v48 row_ror:8 row_mask:0xf bank_mask:0xf
	v_mov_b32_dpp v241, v49 row_ror:8 row_mask:0xf bank_mask:0xf
	v_mov_b32_dpp v242, v50 row_ror:8 row_mask:0xf bank_mask:0xf
	v_mov_b32_dpp v243, v51 row_ror:8 row_mask:0xf bank_mask:0xf
	v_mov_b32_dpp v48, v52 row_ror:8 row_mask:0xf bank_mask:0x3
	v_mov_b32_dpp v49, v53 row_ror:8 row_mask:0xf bank_mask:0x3
	v_mov_b32_dpp v50, v54 row_ror:8 row_mask:0xf bank_mask:0x3
	v_mov_b32_dpp v51, v55 row_ror:8 row_mask:0xf bank_mask:0x3
	v_mov_b32_dpp v52, v240 quad_perm:[0,1,2,3] row_mask:0xf bank_mask:0xc
	v_mov_b32_dpp v53, v241 quad_perm:[0,1,2,3] row_mask:0xf bank_mask:0xc
	v_mov_b32_dpp v54, v242 quad_perm:[0,1,2,3] row_mask:0xf bank_mask:0xc
	v_mov_b32_dpp v55, v243 quad_perm:[0,1,2,3] row_mask:0xf bank_mask:0xc
	s_waitcnt vmcnt(48)
	v_pk_add_f32 v[60:61], v[60:61], v[220:221]
	v_pk_add_f32 v[62:63], v[62:63], v[222:223]
	v_pk_add_f32 v[56:57], v[56:57], v[226:227]
	v_pk_add_f32 v[58:59], v[58:59], v[228:229]
	v_pk_add_f32 v[52:53], v[52:53], v[230:231]
	v_pk_add_f32 v[54:55], v[54:55], v[232:233]
	v_pk_add_f32 v[48:49], v[48:49], v[236:237]
	v_pk_add_f32 v[50:51], v[50:51], v[238:239]
	v_add_u32_e32 v252, 0x80000, v144
	v_add_u32_e32 v253, 0x8000, v252
	global_store_dwordx4 v252, v[60:63], s[54:55] nt
	global_store_dwordx4 v253, v[56:59], s[54:55] nt
	global_store_dwordx4 v252, v[52:55], s[54:55] offset:512 nt
	global_store_dwordx4 v253, v[48:51], s[54:55] offset:512 nt
	v_cvt_pk_bf16_f32 v240, v60, v61
	v_cvt_pk_bf16_f32 v241, v62, v63
	v_cvt_pk_bf16_f32 v242, v56, v57
	v_cvt_pk_bf16_f32 v243, v58, v59
	v_cvt_pk_bf16_f32 v244, v52, v53
	v_cvt_pk_bf16_f32 v245, v54, v55
	v_cvt_pk_bf16_f32 v246, v48, v49
	v_cvt_pk_bf16_f32 v247, v50, v51
	v_lshrrev_b32_e32 v254, 1, v252
	v_lshrrev_b32_e32 v253, 1, v253
	global_store_dwordx2 v254, v[240:241], s[40:41]
	global_store_dwordx2 v253, v[242:243], s[40:41]
	global_store_dwordx2 v254, v[244:245], s[40:41] offset:256
	global_store_dwordx2 v253, v[246:247], s[40:41] offset:256
	v_mul_f32_e32 v248, v60, v60
	v_mul_f32_e32 v249, v56, v56
	v_fmac_f32_e32 v248, v61, v61
	v_fmac_f32_e32 v249, v57, v57
	v_fmac_f32_e32 v248, v62, v62
	v_fmac_f32_e32 v249, v58, v58
	v_fmac_f32_e32 v248, v63, v63
	v_fmac_f32_e32 v249, v59, v59
	v_fmac_f32_e32 v248, v52, v52
	v_fmac_f32_e32 v249, v48, v48
	v_fmac_f32_e32 v248, v53, v53
	v_fmac_f32_e32 v249, v49, v49
	v_fmac_f32_e32 v248, v54, v54
	v_fmac_f32_e32 v249, v50, v50
	v_fmac_f32_e32 v248, v55, v55
	v_fmac_f32_e32 v249, v51, v51
	s_nop 1
	v_mov_b32_dpp v240, v248 row_ror:8 row_mask:0xf bank_mask:0xf
	v_mov_b32_dpp v241, v249 row_ror:8 row_mask:0xf bank_mask:0xf
	s_nop 0
	v_add_f32_e32 v248, v248, v240
	v_add_f32_e32 v249, v249, v241
	s_nop 1
	v_mov_b32_dpp v248, v249 quad_perm:[0,1,2,3] row_mask:0xf bank_mask:0xc
	ds_bpermute_b32 v249, v250, v248
	s_waitcnt lgkmcnt(0)
	v_add_f32_e32 v248, v248, v249
	ds_bpermute_b32 v249, v251, v248
	v_add_u32_e32 v254, 0x2000, v147
	s_waitcnt lgkmcnt(0)
	v_add_f32_e32 v248, v248, v249
	s_and_saveexec_b64 s[62:63], s[0:1]
	global_store_dword v254, v248, s[6:7]
	s_or_b64 exec, exec, s[62:63]
	v_mov_b32_dpp v240, v40 row_ror:8 row_mask:0xf bank_mask:0xf
	v_mov_b32_dpp v241, v41 row_ror:8 row_mask:0xf bank_mask:0xf
	v_mov_b32_dpp v242, v42 row_ror:8 row_mask:0xf bank_mask:0xf
	v_mov_b32_dpp v243, v43 row_ror:8 row_mask:0xf bank_mask:0xf
	v_mov_b32_dpp v40, v44 row_ror:8 row_mask:0xf bank_mask:0x3
	v_mov_b32_dpp v41, v45 row_ror:8 row_mask:0xf bank_mask:0x3
	v_mov_b32_dpp v42, v46 row_ror:8 row_mask:0xf bank_mask:0x3
	v_mov_b32_dpp v43, v47 row_ror:8 row_mask:0xf bank_mask:0x3
	v_mov_b32_dpp v44, v240 quad_perm:[0,1,2,3] row_mask:0xf bank_mask:0xc
	v_mov_b32_dpp v45, v241 quad_perm:[0,1,2,3] row_mask:0xf bank_mask:0xc
	v_mov_b32_dpp v46, v242 quad_perm:[0,1,2,3] row_mask:0xf bank_mask:0xc
	v_mov_b32_dpp v47, v243 quad_perm:[0,1,2,3] row_mask:0xf bank_mask:0xc
	v_mov_b32_dpp v240, v32 row_ror:8 row_mask:0xf bank_mask:0xf
	v_mov_b32_dpp v241, v33 row_ror:8 row_mask:0xf bank_mask:0xf
	v_mov_b32_dpp v242, v34 row_ror:8 row_mask:0xf bank_mask:0xf
	v_mov_b32_dpp v243, v35 row_ror:8 row_mask:0xf bank_mask:0xf
	v_mov_b32_dpp v32, v36 row_ror:8 row_mask:0xf bank_mask:0x3
	v_mov_b32_dpp v33, v37 row_ror:8 row_mask:0xf bank_mask:0x3
	v_mov_b32_dpp v34, v38 row_ror:8 row_mask:0xf bank_mask:0x3
	v_mov_b32_dpp v35, v39 row_ror:8 row_mask:0xf bank_mask:0x3
	v_mov_b32_dpp v36, v240 quad_perm:[0,1,2,3] row_mask:0xf bank_mask:0xc
	v_mov_b32_dpp v37, v241 quad_perm:[0,1,2,3] row_mask:0xf bank_mask:0xc
	v_mov_b32_dpp v38, v242 quad_perm:[0,1,2,3] row_mask:0xf bank_mask:0xc
	v_mov_b32_dpp v39, v243 quad_perm:[0,1,2,3] row_mask:0xf bank_mask:0xc
	s_waitcnt vmcnt(44)
; DI unsigned cvt_pk(float lo, float hi) { const f32x2 v = {lo, hi}; return __builtin_bit_cast(unsigned, __builtin_convertvector(v, bf16v2)); }
;     __device__ __forceinline__ void operator()(const f32x4 (&acc)[2][2][4][2], const Unit& u, int wr, int wc, int fr, int fq) const {
;         const int col0 = u.pn * 256 + wc * 32 + 8 * fq, rowbase = u.pm * 256 + wr * 64 + fr;
; #pragma unroll
;         for (int ai = 0; ai < 2; ++ai)
; #pragma unroll
;             for (int m = 0; m < 4; ++m) {
;                 const int row = rowbase + ai * 128 + m * 16; const size_t off = (size_t)row * DM + col0;
;                 float q = 0.f;
; #pragma unroll
;                 for (int bj = 0; bj < 2; ++bj) {
;                     const f32x4 r0 = *(const f32x4*)(resid + off + bj * 128), r1 = *(const f32x4*)(resid + off + bj * 128 + 4);
;                     const f32x4 o0 = r0 + acc[ai][bj][m][0], o1 = r1 + acc[ai][bj][m][1];
;                     *(f32x4*)(out + off + bj * 128) = o0; *(f32x4*)(out + off + bj * 128 + 4) = o1;
;                     if (xb) {
;                         u32x4 w; w.x = cvt_pk(o0[0], o0[1]); w.y = cvt_pk(o0[2], o0[3]); w.z = cvt_pk(o1[0], o1[1]); w.w = cvt_pk(o1[2], o1[3]);
;                         *(u32x4*)(xb + off + bj * 128) = w;
;                         q += (o0[0] * o0[0] + o0[1] * o0[1]) + (o0[2] * o0[2] + o0[3] * o0[3]) + (o1[0] * o1[0] + o1[1] * o1[1]) + (o1[2] * o1[2] + o1[3] * o1[3]);
;                     }
;                 }
;                 if (xb) { q += __shfl_xor(q, 16); q += __shfl_xor(q, 32); if (fq == 0) ssq[(size_t)row * 16 + u.pn * 4 + wc] = q; }
	v_pk_add_f32 v[44:45], v[44:45], v[156:157]
	v_pk_add_f32 v[46:47], v[46:47], v[158:159]
	v_pk_add_f32 v[40:41], v[40:41], v[160:161]
	v_pk_add_f32 v[42:43], v[42:43], v[162:163]
	v_pk_add_f32 v[36:37], v[36:37], v[164:165]
	v_pk_add_f32 v[38:39], v[38:39], v[166:167]
	v_pk_add_f32 v[32:33], v[32:33], v[168:169]
	v_pk_add_f32 v[34:35], v[34:35], v[170:171]
	v_add_u32_e32 v252, 0x90000, v144
	v_add_u32_e32 v253, 0x8000, v252
	global_store_dwordx4 v252, v[44:47], s[54:55] nt
	global_store_dwordx4 v253, v[40:43], s[54:55] nt
	global_store_dwordx4 v252, v[36:39], s[54:55] offset:512 nt
	global_store_dwordx4 v253, v[32:35], s[54:55] offset:512 nt
	v_cvt_pk_bf16_f32 v240, v44, v45
	v_cvt_pk_bf16_f32 v241, v46, v47
	v_cvt_pk_bf16_f32 v242, v40, v41
	v_cvt_pk_bf16_f32 v243, v42, v43
	v_cvt_pk_bf16_f32 v244, v36, v37
	v_cvt_pk_bf16_f32 v245, v38, v39
	v_cvt_pk_bf16_f32 v246, v32, v33
	v_cvt_pk_bf16_f32 v247, v34, v35
	v_lshrrev_b32_e32 v254, 1, v252
	v_lshrrev_b32_e32 v253, 1, v253
	global_store_dwordx2 v254, v[240:241], s[40:41]
	global_store_dwordx2 v253, v[242:243], s[40:41]
	global_store_dwordx2 v254, v[244:245], s[40:41] offset:256
	global_store_dwordx2 v253, v[246:247], s[40:41] offset:256
	v_mul_f32_e32 v248, v44, v44
	v_mul_f32_e32 v249, v40, v40
	v_fmac_f32_e32 v248, v45, v45
	v_fmac_f32_e32 v249, v41, v41
	v_fmac_f32_e32 v248, v46, v46
	v_fmac_f32_e32 v249, v42, v42
	v_fmac_f32_e32 v248, v47, v47
	v_fmac_f32_e32 v249, v43, v43
	v_fmac_f32_e32 v248, v36, v36
	v_fmac_f32_e32 v249, v32, v32
	v_fmac_f32_e32 v248, v37, v37
	v_fmac_f32_e32 v249, v33, v33
	v_fmac_f32_e32 v248, v38, v38
	v_fmac_f32_e32 v249, v34, v34
	v_fmac_f32_e32 v248, v39, v39
	v_fmac_f32_e32 v249, v35, v35
	s_nop 1
	v_mov_b32_dpp v240, v248 row_ror:8 row_mask:0xf bank_mask:0xf
	v_mov_b32_dpp v241, v249 row_ror:8 row_mask:0xf bank_mask:0xf
	s_nop 0
	v_add_f32_e32 v248, v248, v240
	v_add_f32_e32 v249, v249, v241
	s_nop 1
	v_mov_b32_dpp v248, v249 quad_perm:[0,1,2,3] row_mask:0xf bank_mask:0xc
	ds_bpermute_b32 v249, v250, v248
	s_waitcnt lgkmcnt(0)
	v_add_f32_e32 v248, v248, v249
	ds_bpermute_b32 v249, v251, v248
	v_add_u32_e32 v254, 0x2400, v147
	s_waitcnt lgkmcnt(0)
	v_add_f32_e32 v248, v248, v249
	s_and_saveexec_b64 s[62:63], s[0:1]
	global_store_dword v254, v248, s[6:7]
	s_or_b64 exec, exec, s[62:63]
	v_mov_b32_dpp v240, v24 row_ror:8 row_mask:0xf bank_mask:0xf
	v_mov_b32_dpp v241, v25 row_ror:8 row_mask:0xf bank_mask:0xf
	v_mov_b32_dpp v242, v26 row_ror:8 row_mask:0xf bank_mask:0xf
	v_mov_b32_dpp v243, v27 row_ror:8 row_mask:0xf bank_mask:0xf
	v_mov_b32_dpp v24, v28 row_ror:8 row_mask:0xf bank_mask:0x3
	v_mov_b32_dpp v25, v29 row_ror:8 row_mask:0xf bank_mask:0x3
	v_mov_b32_dpp v26, v30 row_ror:8 row_mask:0xf bank_mask:0x3
	v_mov_b32_dpp v27, v31 row_ror:8 row_mask:0xf bank_mask:0x3
	v_mov_b32_dpp v28, v240 quad_perm:[0,1,2,3] row_mask:0xf bank_mask:0xc
	v_mov_b32_dpp v29, v241 quad_perm:[0,1,2,3] row_mask:0xf bank_mask:0xc
	v_mov_b32_dpp v30, v242 quad_perm:[0,1,2,3] row_mask:0xf bank_mask:0xc
	v_mov_b32_dpp v31, v243 quad_perm:[0,1,2,3] row_mask:0xf bank_mask:0xc
	v_mov_b32_dpp v240, v16 row_ror:8 row_mask:0xf bank_mask:0xf
	v_mov_b32_dpp v241, v17 row_ror:8 row_mask:0xf bank_mask:0xf
	v_mov_b32_dpp v242, v18 row_ror:8 row_mask:0xf bank_mask:0xf
	v_mov_b32_dpp v243, v19 row_ror:8 row_mask:0xf bank_mask:0xf
	v_mov_b32_dpp v16, v20 row_ror:8 row_mask:0xf bank_mask:0x3
	v_mov_b32_dpp v17, v21 row_ror:8 row_mask:0xf bank_mask:0x3
	v_mov_b32_dpp v18, v22 row_ror:8 row_mask:0xf bank_mask:0x3
	v_mov_b32_dpp v19, v23 row_ror:8 row_mask:0xf bank_mask:0x3
	v_mov_b32_dpp v20, v240 quad_perm:[0,1,2,3] row_mask:0xf bank_mask:0xc
	v_mov_b32_dpp v21, v241 quad_perm:[0,1,2,3] row_mask:0xf bank_mask:0xc
	v_mov_b32_dpp v22, v242 quad_perm:[0,1,2,3] row_mask:0xf bank_mask:0xc
	v_mov_b32_dpp v23, v243 quad_perm:[0,1,2,3] row_mask:0xf bank_mask:0xc
	s_waitcnt vmcnt(40)
	v_pk_add_f32 v[28:29], v[28:29], v[172:173]
	v_pk_add_f32 v[30:31], v[30:31], v[174:175]
	v_pk_add_f32 v[24:25], v[24:25], v[176:177]
	v_pk_add_f32 v[26:27], v[26:27], v[178:179]
	v_pk_add_f32 v[20:21], v[20:21], v[180:181]
	v_pk_add_f32 v[22:23], v[22:23], v[182:183]
	v_pk_add_f32 v[16:17], v[16:17], v[184:185]
	v_pk_add_f32 v[18:19], v[18:19], v[186:187]
	v_add_u32_e32 v252, 0xa0000, v144
	v_add_u32_e32 v253, 0x8000, v252
	global_store_dwordx4 v252, v[28:31], s[54:55] nt
	global_store_dwordx4 v253, v[24:27], s[54:55] nt
	global_store_dwordx4 v252, v[20:23], s[54:55] offset:512 nt
	global_store_dwordx4 v253, v[16:19], s[54:55] offset:512 nt
	v_cvt_pk_bf16_f32 v240, v28, v29
	v_cvt_pk_bf16_f32 v241, v30, v31
	v_cvt_pk_bf16_f32 v242, v24, v25
	v_cvt_pk_bf16_f32 v243, v26, v27
	v_cvt_pk_bf16_f32 v244, v20, v21
	v_cvt_pk_bf16_f32 v245, v22, v23
	v_cvt_pk_bf16_f32 v246, v16, v17
	v_cvt_pk_bf16_f32 v247, v18, v19
	v_lshrrev_b32_e32 v254, 1, v252
	v_lshrrev_b32_e32 v253, 1, v253
	global_store_dwordx2 v254, v[240:241], s[40:41]
	global_store_dwordx2 v253, v[242:243], s[40:41]
	global_store_dwordx2 v254, v[244:245], s[40:41] offset:256
	global_store_dwordx2 v253, v[246:247], s[40:41] offset:256
	v_mul_f32_e32 v248, v28, v28
	v_mul_f32_e32 v249, v24, v24
	v_fmac_f32_e32 v248, v29, v29
	v_fmac_f32_e32 v249, v25, v25
	v_fmac_f32_e32 v248, v30, v30
	v_fmac_f32_e32 v249, v26, v26
	v_fmac_f32_e32 v248, v31, v31
	v_fmac_f32_e32 v249, v27, v27
	v_fmac_f32_e32 v248, v20, v20
	v_fmac_f32_e32 v249, v16, v16
	v_fmac_f32_e32 v248, v21, v21
	v_fmac_f32_e32 v249, v17, v17
	v_fmac_f32_e32 v248, v22, v22
	v_fmac_f32_e32 v249, v18, v18
	v_fmac_f32_e32 v248, v23, v23
	v_fmac_f32_e32 v249, v19, v19
	s_nop 1
	v_mov_b32_dpp v240, v248 row_ror:8 row_mask:0xf bank_mask:0xf
	v_mov_b32_dpp v241, v249 row_ror:8 row_mask:0xf bank_mask:0xf
	s_nop 0
	v_add_f32_e32 v248, v248, v240
	v_add_f32_e32 v249, v249, v241
	s_nop 1
	v_mov_b32_dpp v248, v249 quad_perm:[0,1,2,3] row_mask:0xf bank_mask:0xc
	ds_bpermute_b32 v249, v250, v248
	s_waitcnt lgkmcnt(0)
; #define PG8_BAR __builtin_amdgcn_s_barrier()
; DI unsigned cvt_pk(float lo, float hi) { const f32x2 v = {lo, hi}; return __builtin_bit_cast(unsigned, __builtin_convertvector(v, bf16v2)); }
; template <class Epi, class Sched, bool ALIGN_EPI = false, bool SP2 = false>
; __device__ __forceinline__ void gemm_phase(PG8_LAS unsigned char* lds, const Gemm g, const Sched& S, const Epi& E) {
;     ...
;         if (!has_next) break;
; #pragma unroll
;         for (int a = 0; a < 2; ++a)
; #pragma unroll
;             for (int b = 0; b < 2; ++b)
; #pragma unroll
;                 for (int m = 0; m < 4; ++m)
; #pragma unroll
;                     for (int n = 0; n < 2; ++n) acc[a][b][m][n] = (f32x4){0.f, 0.f, 0.f, 0.f};
;         cur = nxt; cA = nA; cB = nB; ++ui;
;         if constexpr (ALIGN_EPI) { if (wr == 1) PG8_BAR; }
;     __device__ __forceinline__ void operator()(const f32x4 (&acc)[2][2][4][2], const Unit& u, int wr, int wc, int fr, int fq) const {
;         const int col0 = u.pn * 256 + wc * 32 + 8 * fq, rowbase = u.pm * 256 + wr * 64 + fr;
; #pragma unroll
;         for (int ai = 0; ai < 2; ++ai)
; #pragma unroll
;             for (int m = 0; m < 4; ++m) {
;                 const int row = rowbase + ai * 128 + m * 16; const size_t off = (size_t)row * DM + col0;
;                 float q = 0.f;
; #pragma unroll
;                 for (int bj = 0; bj < 2; ++bj) {
;                     const f32x4 r0 = *(const f32x4*)(resid + off + bj * 128), r1 = *(const f32x4*)(resid + off + bj * 128 + 4);
;                     const f32x4 o0 = r0 + acc[ai][bj][m][0], o1 = r1 + acc[ai][bj][m][1];
;                     *(f32x4*)(out + off + bj * 128) = o0; *(f32x4*)(out + off + bj * 128 + 4) = o1;
;                     if (xb) {
;                         u32x4 w; w.x = cvt_pk(o0[0], o0[1]); w.y = cvt_pk(o0[2], o0[3]); w.z = cvt_pk(o1[0], o1[1]); w.w = cvt_pk(o1[2], o1[3]);
;                         *(u32x4*)(xb + off + bj * 128) = w;
;                         q += (o0[0] * o0[0] + o0[1] * o0[1]) + (o0[2] * o0[2] + o0[3] * o0[3]) + (o1[0] * o1[0] + o1[1] * o1[1]) + (o1[2] * o1[2] + o1[3] * o1[3]);
;                     }
;                 }
;                 if (xb) { q += __shfl_xor(q, 16); q += __shfl_xor(q, 32); if (fq == 0) ssq[(size_t)row * 16 + u.pn * 4 + wc] = q; }
	v_add_f32_e32 v248, v248, v249
	ds_bpermute_b32 v249, v251, v248
	v_add_u32_e32 v254, 0x2800, v147
	s_waitcnt lgkmcnt(0)
	v_add_f32_e32 v248, v248, v249
	s_and_saveexec_b64 s[62:63], s[0:1]
	global_store_dword v254, v248, s[6:7]
	s_or_b64 exec, exec, s[62:63]
	v_mov_b32_dpp v240, v8 row_ror:8 row_mask:0xf bank_mask:0xf
	v_mov_b32_dpp v241, v9 row_ror:8 row_mask:0xf bank_mask:0xf
	v_mov_b32_dpp v242, v10 row_ror:8 row_mask:0xf bank_mask:0xf
	v_mov_b32_dpp v243, v11 row_ror:8 row_mask:0xf bank_mask:0xf
	v_mov_b32_dpp v8, v12 row_ror:8 row_mask:0xf bank_mask:0x3
	v_mov_b32_dpp v9, v13 row_ror:8 row_mask:0xf bank_mask:0x3
	v_mov_b32_dpp v10, v14 row_ror:8 row_mask:0xf bank_mask:0x3
	v_mov_b32_dpp v11, v15 row_ror:8 row_mask:0xf bank_mask:0x3
	v_mov_b32_dpp v12, v240 quad_perm:[0,1,2,3] row_mask:0xf bank_mask:0xc
	v_mov_b32_dpp v13, v241 quad_perm:[0,1,2,3] row_mask:0xf bank_mask:0xc
	v_mov_b32_dpp v14, v242 quad_perm:[0,1,2,3] row_mask:0xf bank_mask:0xc
	v_mov_b32_dpp v15, v243 quad_perm:[0,1,2,3] row_mask:0xf bank_mask:0xc
	v_mov_b32_dpp v240, v0 row_ror:8 row_mask:0xf bank_mask:0xf
	v_mov_b32_dpp v241, v1 row_ror:8 row_mask:0xf bank_mask:0xf
	v_mov_b32_dpp v242, v2 row_ror:8 row_mask:0xf bank_mask:0xf
	v_mov_b32_dpp v243, v3 row_ror:8 row_mask:0xf bank_mask:0xf
	v_mov_b32_dpp v0, v4 row_ror:8 row_mask:0xf bank_mask:0x3
	v_mov_b32_dpp v1, v5 row_ror:8 row_mask:0xf bank_mask:0x3
	v_mov_b32_dpp v2, v6 row_ror:8 row_mask:0xf bank_mask:0x3
	v_mov_b32_dpp v3, v7 row_ror:8 row_mask:0xf bank_mask:0x3
	v_mov_b32_dpp v4, v240 quad_perm:[0,1,2,3] row_mask:0xf bank_mask:0xc
	v_mov_b32_dpp v5, v241 quad_perm:[0,1,2,3] row_mask:0xf bank_mask:0xc
	v_mov_b32_dpp v6, v242 quad_perm:[0,1,2,3] row_mask:0xf bank_mask:0xc
	v_mov_b32_dpp v7, v243 quad_perm:[0,1,2,3] row_mask:0xf bank_mask:0xc
	s_waitcnt vmcnt(36)
	v_pk_add_f32 v[12:13], v[12:13], v[188:189]
	v_pk_add_f32 v[14:15], v[14:15], v[190:191]
	v_pk_add_f32 v[8:9], v[8:9], v[192:193]
	v_pk_add_f32 v[10:11], v[10:11], v[194:195]
	v_pk_add_f32 v[4:5], v[4:5], v[196:197]
	v_pk_add_f32 v[6:7], v[6:7], v[198:199]
	v_pk_add_f32 v[0:1], v[0:1], v[200:201]
	v_pk_add_f32 v[2:3], v[2:3], v[202:203]
	v_add_u32_e32 v252, 0xb0000, v144
	v_add_u32_e32 v253, 0x8000, v252
	global_store_dwordx4 v252, v[12:15], s[54:55] nt
	global_store_dwordx4 v253, v[8:11], s[54:55] nt
	global_store_dwordx4 v252, v[4:7], s[54:55] offset:512 nt
	global_store_dwordx4 v253, v[0:3], s[54:55] offset:512 nt
	v_cvt_pk_bf16_f32 v240, v12, v13
	v_cvt_pk_bf16_f32 v241, v14, v15
	v_cvt_pk_bf16_f32 v242, v8, v9
	v_cvt_pk_bf16_f32 v243, v10, v11
	v_cvt_pk_bf16_f32 v244, v4, v5
	v_cvt_pk_bf16_f32 v245, v6, v7
	v_cvt_pk_bf16_f32 v246, v0, v1
	v_cvt_pk_bf16_f32 v247, v2, v3
	v_lshrrev_b32_e32 v254, 1, v252
	v_lshrrev_b32_e32 v253, 1, v253
	global_store_dwordx2 v254, v[240:241], s[40:41]
	global_store_dwordx2 v253, v[242:243], s[40:41]
	global_store_dwordx2 v254, v[244:245], s[40:41] offset:256
	global_store_dwordx2 v253, v[246:247], s[40:41] offset:256
	v_mul_f32_e32 v248, v12, v12
	v_mul_f32_e32 v249, v8, v8
	v_fmac_f32_e32 v248, v13, v13
	v_fmac_f32_e32 v249, v9, v9
	v_fmac_f32_e32 v248, v14, v14
	v_fmac_f32_e32 v249, v10, v10
	v_fmac_f32_e32 v248, v15, v15
	v_fmac_f32_e32 v249, v11, v11
	v_fmac_f32_e32 v248, v4, v4
	v_fmac_f32_e32 v249, v0, v0
	v_fmac_f32_e32 v248, v5, v5
	v_fmac_f32_e32 v249, v1, v1
	v_fmac_f32_e32 v248, v6, v6
	v_fmac_f32_e32 v249, v2, v2
	v_fmac_f32_e32 v248, v7, v7
	v_fmac_f32_e32 v249, v3, v3
	s_nop 1
	v_mov_b32_dpp v240, v248 row_ror:8 row_mask:0xf bank_mask:0xf
	v_mov_b32_dpp v241, v249 row_ror:8 row_mask:0xf bank_mask:0xf
	s_nop 0
	v_add_f32_e32 v248, v248, v240
	v_add_f32_e32 v249, v249, v241
	s_nop 1
	v_mov_b32_dpp v248, v249 quad_perm:[0,1,2,3] row_mask:0xf bank_mask:0xc
	ds_bpermute_b32 v249, v250, v248
	s_waitcnt lgkmcnt(0)
	v_add_f32_e32 v248, v248, v249
	ds_bpermute_b32 v249, v251, v248
	v_add_u32_e32 v254, 0x2c00, v147
	s_waitcnt lgkmcnt(0)
	v_add_f32_e32 v248, v248, v249
	s_and_saveexec_b64 s[62:63], s[0:1]
	global_store_dword v254, v248, s[6:7]
	s_or_b64 exec, exec, s[62:63]
	s_andn2_b64 vcc, exec, s[4:5]
	s_mov_b64 s[4:5], -1
	s_cbranch_vccnz .LBB0_742
	s_andn2_b64 vcc, exec, s[10:11]
	s_cbranch_vccnz .LBB0_741
	s_barrier
	s_branch .LBB0_741
